# reads-first load segment plus removal of the redundant post-barrier lgkmcnt(0) in the GEMM compute segments
# baseline (speedup 1.0000x reference)
; #define PG8_STAGE(bufoff, gbase, voff) do { _Pragma("unroll") for (int _i = 0; _i < 2; ++_i) \
;         __builtin_amdgcn_global_load_lds((const unsigned*)((const char*)(gbase) + (voff)[_i]), (LAS unsigned*)(lds + (bufoff) + ldsw + _i * 8192), 16, 0, 0); } while (0)
; #define PG8_LDA(dst, b, h) do { _Pragma("unroll") for (int m = 0; m < 4; ++m) _Pragma("unroll") for (int k = 0; k < 2; ++k) dst[m][k] = *(const LAS bf16x8*)(lds + PG8_SA(b, h) + aoff + m * 2048 + k * 1024); } while (0)
; #define PG8_LDB(dst, b, h) do { _Pragma("unroll") for (int n = 0; n < 2; ++n) _Pragma("unroll") for (int k = 0; k < 2; ++k) dst[n][k] = *(const LAS bf16x8*)(lds + PG8_SB(b, h) + boff + n * 2048 + k * 1024); } while (0)
; #define PG8_MMA(ai, bj, At, Bt) do { __builtin_amdgcn_s_setprio(1); _Pragma("unroll") for (int m = 0; m < 4; ++m) _Pragma("unroll") for (int n = 0; n < 2; ++n) _Pragma("unroll") for (int k = 0; k < 2; ++k) \
;         acc[ai][bj][m][n] = __builtin_amdgcn_mfma_f32_16x16x32_bf16(Bt[n][k], At[m][k], acc[ai][bj][m][n], 0, 0, 0); __builtin_amdgcn_s_setprio(0); } while (0)
; #define PG8_WAIT_V(n) asm volatile("s_waitcnt vmcnt(" #n ")" ::: "memory")
; #define PG8_WAIT_L(n) asm volatile("s_waitcnt lgkmcnt(" #n ")" ::: "memory")
; #define PG8_BAR __builtin_amdgcn_s_barrier()
; #define PG8_SCHED __builtin_amdgcn_sched_barrier(0)
; __device__ __forceinline__ void gemm_phase(LAS unsigned char* lds, const GemmD g, const Sched& S, const Epi& E) {
;     ...
;         for (int t = 0; t < nt; t += 2) {
;             const bool last = (t == nt - 2);
;             const char* a1 = cA + (size_t)(t + 1) * kstep;
;             const char* a2 = last ? nA : cA + (size_t)(t + 2) * kstep; const char* b2 = last ? nB : cB + (size_t)(t + 2) * kstep;
;             const char* a3 = a2 + kstep; const char* b3 = b2 + kstep;
;             PG8_LDB(B0, 0, 0); PG8_LDB(B1, 0, 1); PG8_SCHED; PG8_LDA(At, 0, 0); PG8_STAGE(PG8_SA(1, 1), a1 + hstepA, voffA);
;             PG8_WAIT_V(8); PG8_WAIT_L(0); PG8_BAR; PG8_MMA(0, 0, At, B0); PG8_MMA(0, 1, At, B1); PG8_BAR; PG8_SCHED;
;             PG8_LDA(At, 0, 1); PG8_STAGE(PG8_SB(0, 0), b2, voffB); PG8_STAGE(PG8_SB(0, 1), b2 + hstepB, voffB); PG8_STAGE(PG8_SA(0, 0), a2, voffA);
;             PG8_WAIT_V(8); PG8_WAIT_L(0); PG8_BAR; PG8_MMA(1, 0, At, B0); PG8_MMA(1, 1, At, B1); PG8_BAR; PG8_SCHED;
.Lprio_done:
	v_add_u32_e32 v240, 0x10000, v160
	v_add_u32_e32 v241, 0x14000, v160
	v_add_u32_e32 v242, 0x18000, v160
	v_add_u32_e32 v243, 0x1c000, v160
	ds_read_b128 v[130:133], v240
	ds_read_b128 v[146:149], v240 offset:1024
	ds_read_b128 v[150:153], v240 offset:2048
	ds_read_b128 v[154:157], v240 offset:3072
	ds_read_b128 v[162:165], v241
	ds_read_b128 v[166:169], v241 offset:1024
	ds_read_b128 v[170:173], v241 offset:2048
	ds_read_b128 v[174:177], v241 offset:3072
	s_add_i32 m0, s31, 0xc000
	ds_read_b128 v[182:185], v161
	ds_read_b128 v[186:189], v161 offset:1024
	ds_read_b128 v[190:193], v161 offset:2048
	ds_read_b128 v[216:219], v161 offset:3072
	ds_read_b128 v[220:223], v161 offset:4096
	ds_read_b128 v[224:227], v161 offset:5120
	ds_read_b128 v[228:231], v161 offset:6144
	ds_read_b128 v[236:239], v161 offset:7168
	global_load_lds_dwordx4 v142, s[8:9]
	s_add_i32 m0, s31, 0xe000
	s_nop 0
	global_load_lds_dwordx4 v144, s[8:9]
	s_add_i32 s92, s26, 2
	s_add_u32 s93, s8, 0x80
	s_addc_u32 s27, s9, 0
	s_add_i32 s22, 0, 0x10000
	s_cmp_eq_u32 s11, s26
	s_cselect_b32 s27, s1, s27
	s_cselect_b32 s26, s0, s93
	s_cselect_b32 vcc_hi, s17, s35
	s_cselect_b32 vcc_lo, s16, s34
	s_add_i32 s23, 0, 0x14000
	s_waitcnt vmcnt(8)
	s_waitcnt lgkmcnt(0)
	s_barrier
	v_mfma_f32_16x16x32_bf16 v[126:129], v[130:133], v[182:185], 0
	v_mfma_f32_16x16x32_bf16 v[122:125], v[150:153], v[182:185], 0
	v_mfma_f32_16x16x32_bf16 v[110:113], v[130:133], v[190:193], 0
	v_mfma_f32_16x16x32_bf16 v[106:109], v[150:153], v[190:193], 0
	v_mfma_f32_16x16x32_bf16 v[94:97], v[130:133], v[220:223], 0
	v_mfma_f32_16x16x32_bf16 v[90:93], v[150:153], v[220:223], 0
	v_mfma_f32_16x16x32_bf16 v[78:81], v[130:133], v[228:231], 0
	v_mfma_f32_16x16x32_bf16 v[74:77], v[150:153], v[228:231], 0
	v_mfma_f32_16x16x32_bf16 v[126:129], v[146:149], v[186:189], v[126:129]
	v_mfma_f32_16x16x32_bf16 v[122:125], v[154:157], v[186:189], v[122:125]
	v_mfma_f32_16x16x32_bf16 v[110:113], v[146:149], v[216:219], v[110:113]
	v_mfma_f32_16x16x32_bf16 v[106:109], v[154:157], v[216:219], v[106:109]
	v_mfma_f32_16x16x32_bf16 v[94:97], v[146:149], v[224:227], v[94:97]
	v_mfma_f32_16x16x32_bf16 v[90:93], v[154:157], v[224:227], v[90:93]
	v_mfma_f32_16x16x32_bf16 v[78:81], v[146:149], v[236:239], v[78:81]
	v_mfma_f32_16x16x32_bf16 v[74:77], v[154:157], v[236:239], v[74:77]
	v_mfma_f32_16x16x32_bf16 v[118:121], v[162:165], v[182:185], 0
	v_mfma_f32_16x16x32_bf16 v[114:117], v[170:173], v[182:185], 0
	v_mfma_f32_16x16x32_bf16 v[102:105], v[162:165], v[190:193], 0
	v_mfma_f32_16x16x32_bf16 v[98:101], v[170:173], v[190:193], 0
	v_mfma_f32_16x16x32_bf16 v[86:89], v[162:165], v[220:223], 0
	v_mfma_f32_16x16x32_bf16 v[82:85], v[170:173], v[220:223], 0
	v_mfma_f32_16x16x32_bf16 v[70:73], v[162:165], v[228:231], 0
	v_mfma_f32_16x16x32_bf16 v[66:69], v[170:173], v[228:231], 0
	v_mfma_f32_16x16x32_bf16 v[118:121], v[166:169], v[186:189], v[118:121]
	v_mfma_f32_16x16x32_bf16 v[114:117], v[174:177], v[186:189], v[114:117]
	v_mfma_f32_16x16x32_bf16 v[102:105], v[166:169], v[216:219], v[102:105]
	v_mfma_f32_16x16x32_bf16 v[98:101], v[174:177], v[216:219], v[98:101]
	v_mfma_f32_16x16x32_bf16 v[86:89], v[166:169], v[224:227], v[86:89]
	v_mfma_f32_16x16x32_bf16 v[82:85], v[174:177], v[224:227], v[82:85]
	v_mfma_f32_16x16x32_bf16 v[70:73], v[166:169], v[236:239], v[70:73]
	v_mfma_f32_16x16x32_bf16 v[66:69], v[174:177], v[236:239], v[66:69]
	s_barrier
	s_add_i32 s22, s22, s30
	s_mov_b32 m0, s22
	ds_read_b128 v[182:185], v161 offset:16384
	ds_read_b128 v[186:189], v161 offset:17408
	ds_read_b128 v[190:193], v161 offset:18432
	ds_read_b128 v[216:219], v161 offset:19456
	ds_read_b128 v[220:223], v161 offset:20480
	ds_read_b128 v[224:227], v161 offset:21504
	ds_read_b128 v[228:231], v161 offset:22528
	ds_read_b128 v[236:239], v161 offset:23552
	global_load_lds_dwordx4 v136, vcc
	s_add_i32 m0, s22, 0x2000
	s_add_i32 s22, s23, s30
	global_load_lds_dwordx4 v140, vcc
	s_mov_b32 m0, s22
	s_nop 0
	global_load_lds_dwordx4 v253, vcc
	s_add_i32 m0, s22, 0x2000
	s_nop 0
	global_load_lds_dwordx4 v254, vcc
	s_mov_b32 m0, s31
	s_nop 0
	global_load_lds_dwordx4 v134, s[26:27]
	s_mov_b32 m0, s14
	s_nop 0
	global_load_lds_dwordx4 v138, s[26:27]
	s_waitcnt vmcnt(8)
	s_waitcnt lgkmcnt(0)
	s_barrier
	v_mfma_f32_16x16x32_bf16 v[62:65], v[130:133], v[182:185], 0
	v_mfma_f32_16x16x32_bf16 v[58:61], v[150:153], v[182:185], 0
	v_mfma_f32_16x16x32_bf16 v[46:49], v[130:133], v[190:193], 0
	v_mfma_f32_16x16x32_bf16 v[42:45], v[150:153], v[190:193], 0
	v_mfma_f32_16x16x32_bf16 v[30:33], v[130:133], v[220:223], 0
	v_mfma_f32_16x16x32_bf16 v[26:29], v[150:153], v[220:223], 0
	v_mfma_f32_16x16x32_bf16 v[14:17], v[130:133], v[228:231], 0
	v_mfma_f32_16x16x32_bf16 v[10:13], v[150:153], v[228:231], 0
	v_mfma_f32_16x16x32_bf16 v[62:65], v[146:149], v[186:189], v[62:65]
	v_mfma_f32_16x16x32_bf16 v[58:61], v[154:157], v[186:189], v[58:61]
	v_mfma_f32_16x16x32_bf16 v[46:49], v[146:149], v[216:219], v[46:49]
	v_mfma_f32_16x16x32_bf16 v[42:45], v[154:157], v[216:219], v[42:45]
	v_mfma_f32_16x16x32_bf16 v[30:33], v[146:149], v[224:227], v[30:33]
	v_mfma_f32_16x16x32_bf16 v[26:29], v[154:157], v[224:227], v[26:29]
	v_mfma_f32_16x16x32_bf16 v[14:17], v[146:149], v[236:239], v[14:17]
	v_mfma_f32_16x16x32_bf16 v[10:13], v[154:157], v[236:239], v[10:13]
	v_mfma_f32_16x16x32_bf16 v[54:57], v[162:165], v[182:185], 0
	v_mfma_f32_16x16x32_bf16 v[50:53], v[170:173], v[182:185], 0
	v_mfma_f32_16x16x32_bf16 v[38:41], v[162:165], v[190:193], 0
	v_mfma_f32_16x16x32_bf16 v[34:37], v[170:173], v[190:193], 0
	v_mfma_f32_16x16x32_bf16 v[22:25], v[162:165], v[220:223], 0
	v_mfma_f32_16x16x32_bf16 v[18:21], v[170:173], v[220:223], 0
	v_mfma_f32_16x16x32_bf16 v[6:9], v[162:165], v[228:231], 0
	v_mfma_f32_16x16x32_bf16 v[2:5], v[170:173], v[228:231], 0
	v_mfma_f32_16x16x32_bf16 v[54:57], v[166:169], v[186:189], v[54:57]
	v_mfma_f32_16x16x32_bf16 v[50:53], v[174:177], v[186:189], v[50:53]
	v_mfma_f32_16x16x32_bf16 v[38:41], v[166:169], v[216:219], v[38:41]
	v_mfma_f32_16x16x32_bf16 v[34:37], v[174:177], v[216:219], v[34:37]
	v_mfma_f32_16x16x32_bf16 v[22:25], v[166:169], v[224:227], v[22:25]
	v_mfma_f32_16x16x32_bf16 v[18:21], v[174:177], v[224:227], v[18:21]
	v_mfma_f32_16x16x32_bf16 v[6:9], v[166:169], v[236:239], v[6:9]
	v_mfma_f32_16x16x32_bf16 v[2:5], v[174:177], v[236:239], v[2:5]
	s_barrier
; #define PG8_STAGE(bufoff, gbase, voff) do { _Pragma("unroll") for (int _i = 0; _i < 2; ++_i) \
;         __builtin_amdgcn_global_load_lds((const unsigned*)((const char*)(gbase) + (voff)[_i]), (LAS unsigned*)(lds + (bufoff) + ldsw + _i * 8192), 16, 0, 0); } while (0)
; #define PG8_LDA(dst, b, h) do { _Pragma("unroll") for (int m = 0; m < 4; ++m) _Pragma("unroll") for (int k = 0; k < 2; ++k) dst[m][k] = *(const LAS bf16x8*)(lds + PG8_SA(b, h) + aoff + m * 2048 + k * 1024); } while (0)
; #define PG8_LDB(dst, b, h) do { _Pragma("unroll") for (int n = 0; n < 2; ++n) _Pragma("unroll") for (int k = 0; k < 2; ++k) dst[n][k] = *(const LAS bf16x8*)(lds + PG8_SB(b, h) + boff + n * 2048 + k * 1024); } while (0)
; #define PG8_MMA(ai, bj, At, Bt) do { __builtin_amdgcn_s_setprio(1); _Pragma("unroll") for (int m = 0; m < 4; ++m) _Pragma("unroll") for (int n = 0; n < 2; ++n) _Pragma("unroll") for (int k = 0; k < 2; ++k) \
;         acc[ai][bj][m][n] = __builtin_amdgcn_mfma_f32_16x16x32_bf16(Bt[n][k], At[m][k], acc[ai][bj][m][n], 0, 0, 0); __builtin_amdgcn_s_setprio(0); } while (0)
; #define PG8_WAIT_V(n) asm volatile("s_waitcnt vmcnt(" #n ")" ::: "memory")
; #define PG8_WAIT_L(n) asm volatile("s_waitcnt lgkmcnt(" #n ")" ::: "memory")
; #define PG8_BAR __builtin_amdgcn_s_barrier()
; #define PG8_SCHED __builtin_amdgcn_sched_barrier(0)
; __device__ __forceinline__ void gemm_phase(LAS unsigned char* lds, const GemmD g, const Sched& S, const Epi& E) {
;     ...
;             PG8_LDB(B0, 1, 0); PG8_LDB(B1, 1, 1); PG8_SCHED; PG8_LDA(At, 1, 0); PG8_STAGE(PG8_SA(0, 1), a2 + hstepA, voffA);
;             PG8_WAIT_V(8); PG8_WAIT_L(0); PG8_BAR; PG8_MMA(0, 0, At, B0); PG8_MMA(0, 1, At, B1); PG8_BAR; PG8_SCHED;
;             PG8_LDA(At, 1, 1); PG8_STAGE(PG8_SB(1, 0), b3, voffB); PG8_STAGE(PG8_SB(1, 1), b3 + hstepB, voffB); PG8_STAGE(PG8_SA(1, 0), a3, voffA);
;             PG8_WAIT_V(8); PG8_WAIT_L(0); PG8_BAR; PG8_MMA(1, 0, At, B0); PG8_MMA(1, 1, At, B1); PG8_BAR; PG8_SCHED;
;         }
	s_add_i32 s22, 0, 0x18000
	s_add_i32 s23, 0, 0x1c000
	ds_read_b128 v[130:133], v242
	ds_read_b128 v[146:149], v242 offset:1024
	ds_read_b128 v[150:153], v242 offset:2048
	ds_read_b128 v[154:157], v242 offset:3072
	ds_read_b128 v[162:165], v243
	ds_read_b128 v[166:169], v243 offset:1024
	ds_read_b128 v[170:173], v243 offset:2048
	ds_read_b128 v[174:177], v243 offset:3072
	s_mov_b32 m0, s15
	ds_read_b128 v[182:185], v161 offset:32768
	ds_read_b128 v[186:189], v161 offset:33792
	ds_read_b128 v[190:193], v161 offset:34816
	ds_read_b128 v[216:219], v161 offset:35840
	ds_read_b128 v[220:223], v161 offset:36864
	ds_read_b128 v[224:227], v161 offset:37888
	ds_read_b128 v[228:231], v161 offset:38912
	ds_read_b128 v[236:239], v161 offset:39936
	global_load_lds_dwordx4 v142, s[26:27]
	s_mov_b32 m0, s10
	s_nop 0
	global_load_lds_dwordx4 v144, s[26:27]
	s_waitcnt vmcnt(8)
	s_waitcnt lgkmcnt(0)
	s_barrier
	v_mfma_f32_16x16x32_bf16 v[126:129], v[130:133], v[182:185], v[126:129]
	v_mfma_f32_16x16x32_bf16 v[122:125], v[150:153], v[182:185], v[122:125]
	v_mfma_f32_16x16x32_bf16 v[110:113], v[130:133], v[190:193], v[110:113]
	v_mfma_f32_16x16x32_bf16 v[106:109], v[150:153], v[190:193], v[106:109]
	v_mfma_f32_16x16x32_bf16 v[94:97], v[130:133], v[220:223], v[94:97]
	v_mfma_f32_16x16x32_bf16 v[90:93], v[150:153], v[220:223], v[90:93]
	v_mfma_f32_16x16x32_bf16 v[78:81], v[130:133], v[228:231], v[78:81]
	v_mfma_f32_16x16x32_bf16 v[74:77], v[150:153], v[228:231], v[74:77]
	v_mfma_f32_16x16x32_bf16 v[126:129], v[146:149], v[186:189], v[126:129]
	v_mfma_f32_16x16x32_bf16 v[122:125], v[154:157], v[186:189], v[122:125]
	v_mfma_f32_16x16x32_bf16 v[110:113], v[146:149], v[216:219], v[110:113]
	v_mfma_f32_16x16x32_bf16 v[106:109], v[154:157], v[216:219], v[106:109]
	v_mfma_f32_16x16x32_bf16 v[94:97], v[146:149], v[224:227], v[94:97]
	v_mfma_f32_16x16x32_bf16 v[90:93], v[154:157], v[224:227], v[90:93]
	v_mfma_f32_16x16x32_bf16 v[78:81], v[146:149], v[236:239], v[78:81]
	v_mfma_f32_16x16x32_bf16 v[74:77], v[154:157], v[236:239], v[74:77]
	v_mfma_f32_16x16x32_bf16 v[118:121], v[162:165], v[182:185], v[118:121]
	v_mfma_f32_16x16x32_bf16 v[114:117], v[170:173], v[182:185], v[114:117]
	v_mfma_f32_16x16x32_bf16 v[102:105], v[162:165], v[190:193], v[102:105]
	v_mfma_f32_16x16x32_bf16 v[98:101], v[170:173], v[190:193], v[98:101]
	v_mfma_f32_16x16x32_bf16 v[86:89], v[162:165], v[220:223], v[86:89]
	v_mfma_f32_16x16x32_bf16 v[82:85], v[170:173], v[220:223], v[82:85]
	v_mfma_f32_16x16x32_bf16 v[70:73], v[162:165], v[228:231], v[70:73]
	v_mfma_f32_16x16x32_bf16 v[66:69], v[170:173], v[228:231], v[66:69]
	v_mfma_f32_16x16x32_bf16 v[118:121], v[166:169], v[186:189], v[118:121]
	v_mfma_f32_16x16x32_bf16 v[114:117], v[174:177], v[186:189], v[114:117]
	v_mfma_f32_16x16x32_bf16 v[102:105], v[166:169], v[216:219], v[102:105]
	v_mfma_f32_16x16x32_bf16 v[98:101], v[174:177], v[216:219], v[98:101]
	v_mfma_f32_16x16x32_bf16 v[86:89], v[166:169], v[224:227], v[86:89]
	v_mfma_f32_16x16x32_bf16 v[82:85], v[174:177], v[224:227], v[82:85]
	v_mfma_f32_16x16x32_bf16 v[70:73], v[166:169], v[236:239], v[70:73]
	v_mfma_f32_16x16x32_bf16 v[66:69], v[174:177], v[236:239], v[66:69]
	s_barrier
	s_add_i32 s22, s22, s30
	s_add_u32 vcc_lo, vcc_lo, s84
	s_addc_u32 vcc_hi, vcc_hi, s85
	s_add_u32 s26, s26, s84
	s_addc_u32 s27, s27, s85
	s_mov_b32 m0, s22
	ds_read_b128 v[182:185], v161 offset:49152
	ds_read_b128 v[186:189], v161 offset:50176
	ds_read_b128 v[190:193], v161 offset:51200
	ds_read_b128 v[216:219], v161 offset:52224
	ds_read_b128 v[220:223], v161 offset:53248
	ds_read_b128 v[224:227], v161 offset:54272
	ds_read_b128 v[228:231], v161 offset:55296
	ds_read_b128 v[236:239], v161 offset:56320
	global_load_lds_dwordx4 v136, vcc
	s_add_i32 m0, s22, 0x2000
	s_add_i32 s22, s23, s30
	global_load_lds_dwordx4 v140, vcc
	s_mov_b32 m0, s22
	s_nop 0
	global_load_lds_dwordx4 v253, vcc
	s_add_i32 m0, s22, 0x2000
	s_nop 0
	global_load_lds_dwordx4 v254, vcc
	s_mov_b32 m0, s18
	s_nop 0
	global_load_lds_dwordx4 v134, s[26:27]
	s_mov_b32 m0, s19
	s_nop 0
	global_load_lds_dwordx4 v138, s[26:27]
	s_waitcnt vmcnt(8)
	s_waitcnt lgkmcnt(0)
	s_barrier
	v_mfma_f32_16x16x32_bf16 v[62:65], v[130:133], v[182:185], v[62:65]
	v_mfma_f32_16x16x32_bf16 v[58:61], v[150:153], v[182:185], v[58:61]
	v_mfma_f32_16x16x32_bf16 v[46:49], v[130:133], v[190:193], v[46:49]
	v_mfma_f32_16x16x32_bf16 v[42:45], v[150:153], v[190:193], v[42:45]
	v_mfma_f32_16x16x32_bf16 v[30:33], v[130:133], v[220:223], v[30:33]
	v_mfma_f32_16x16x32_bf16 v[26:29], v[150:153], v[220:223], v[26:29]
	v_mfma_f32_16x16x32_bf16 v[14:17], v[130:133], v[228:231], v[14:17]
	v_mfma_f32_16x16x32_bf16 v[10:13], v[150:153], v[228:231], v[10:13]
	v_mfma_f32_16x16x32_bf16 v[62:65], v[146:149], v[186:189], v[62:65]
	v_mfma_f32_16x16x32_bf16 v[58:61], v[154:157], v[186:189], v[58:61]
	v_mfma_f32_16x16x32_bf16 v[46:49], v[146:149], v[216:219], v[46:49]
	v_mfma_f32_16x16x32_bf16 v[42:45], v[154:157], v[216:219], v[42:45]
	v_mfma_f32_16x16x32_bf16 v[30:33], v[146:149], v[224:227], v[30:33]
	v_mfma_f32_16x16x32_bf16 v[26:29], v[154:157], v[224:227], v[26:29]
	v_mfma_f32_16x16x32_bf16 v[14:17], v[146:149], v[236:239], v[14:17]
	v_mfma_f32_16x16x32_bf16 v[10:13], v[154:157], v[236:239], v[10:13]
	v_mfma_f32_16x16x32_bf16 v[54:57], v[162:165], v[182:185], v[54:57]
	v_mfma_f32_16x16x32_bf16 v[50:53], v[170:173], v[182:185], v[50:53]
	v_mfma_f32_16x16x32_bf16 v[38:41], v[162:165], v[190:193], v[38:41]
	v_mfma_f32_16x16x32_bf16 v[34:37], v[170:173], v[190:193], v[34:37]
	v_mfma_f32_16x16x32_bf16 v[22:25], v[162:165], v[220:223], v[22:25]
	v_mfma_f32_16x16x32_bf16 v[18:21], v[170:173], v[220:223], v[18:21]
	v_mfma_f32_16x16x32_bf16 v[6:9], v[162:165], v[228:231], v[6:9]
	v_mfma_f32_16x16x32_bf16 v[2:5], v[170:173], v[228:231], v[2:5]
	v_mfma_f32_16x16x32_bf16 v[54:57], v[166:169], v[186:189], v[54:57]
	v_mfma_f32_16x16x32_bf16 v[50:53], v[174:177], v[186:189], v[50:53]
	v_mfma_f32_16x16x32_bf16 v[38:41], v[166:169], v[216:219], v[38:41]
	v_mfma_f32_16x16x32_bf16 v[34:37], v[174:177], v[216:219], v[34:37]
	v_mfma_f32_16x16x32_bf16 v[22:25], v[166:169], v[224:227], v[22:25]
	v_mfma_f32_16x16x32_bf16 v[18:21], v[174:177], v[224:227], v[18:21]
	v_mfma_f32_16x16x32_bf16 v[6:9], v[166:169], v[236:239], v[6:9]
	v_mfma_f32_16x16x32_bf16 v[2:5], v[174:177], v[236:239], v[2:5]
	s_barrier
	s_add_u32 s8, s8, 0x100
	s_addc_u32 s9, s9, 0
	s_add_u32 s34, s34, 0x100
	s_addc_u32 s35, s35, 0
	s_cmp_ge_u32 s92, s12
	s_mov_b32 s26, s92
	s_cbranch_scc0 .LBB0_215
	s_branch .Lgemm_after
; #define PG8_STAGE(bufoff, gbase, voff) do { _Pragma("unroll") for (int _i = 0; _i < 2; ++_i) \
;         __builtin_amdgcn_global_load_lds((const unsigned*)((const char*)(gbase) + (voff)[_i]), (LAS unsigned*)(lds + (bufoff) + ldsw + _i * 8192), 16, 0, 0); } while (0)
; #define PG8_LDA(dst, b, h) do { _Pragma("unroll") for (int m = 0; m < 4; ++m) _Pragma("unroll") for (int k = 0; k < 2; ++k) dst[m][k] = *(const LAS bf16x8*)(lds + PG8_SA(b, h) + aoff + m * 2048 + k * 1024); } while (0)
; #define PG8_LDB(dst, b, h) do { _Pragma("unroll") for (int n = 0; n < 2; ++n) _Pragma("unroll") for (int k = 0; k < 2; ++k) dst[n][k] = *(const LAS bf16x8*)(lds + PG8_SB(b, h) + boff + n * 2048 + k * 1024); } while (0)
; #define PG8_MMA(ai, bj, At, Bt) do { __builtin_amdgcn_s_setprio(1); _Pragma("unroll") for (int m = 0; m < 4; ++m) _Pragma("unroll") for (int n = 0; n < 2; ++n) _Pragma("unroll") for (int k = 0; k < 2; ++k) \
;         acc[ai][bj][m][n] = __builtin_amdgcn_mfma_f32_16x16x32_bf16(Bt[n][k], At[m][k], acc[ai][bj][m][n], 0, 0, 0); __builtin_amdgcn_s_setprio(0); } while (0)
; #define PG8_WAIT_V(n) asm volatile("s_waitcnt vmcnt(" #n ")" ::: "memory")
; #define PG8_WAIT_L(n) asm volatile("s_waitcnt lgkmcnt(" #n ")" ::: "memory")
; #define PG8_BAR __builtin_amdgcn_s_barrier()
; #define PG8_SCHED __builtin_amdgcn_sched_barrier(0)
; __device__ __forceinline__ void gemm_phase(LAS unsigned char* lds, const GemmD g, const Sched& S, const Epi& E) {
;     ...
;         for (int t = 0; t < nt; t += 2) {
;             const bool last = (t == nt - 2);
;             const char* a1 = cA + (size_t)(t + 1) * kstep;
;             const char* a2 = last ? nA : cA + (size_t)(t + 2) * kstep; const char* b2 = last ? nB : cB + (size_t)(t + 2) * kstep;
;             const char* a3 = a2 + kstep; const char* b3 = b2 + kstep;
;             PG8_LDB(B0, 0, 0); PG8_LDB(B1, 0, 1); PG8_SCHED; PG8_LDA(At, 0, 0); PG8_STAGE(PG8_SA(1, 1), a1 + hstepA, voffA);
;             PG8_WAIT_V(8); PG8_WAIT_L(0); PG8_BAR; PG8_MMA(0, 0, At, B0); PG8_MMA(0, 1, At, B1); PG8_BAR; PG8_SCHED;
;             PG8_LDA(At, 0, 1); PG8_STAGE(PG8_SB(0, 0), b2, voffB); PG8_STAGE(PG8_SB(0, 1), b2 + hstepB, voffB); PG8_STAGE(PG8_SA(0, 0), a2, voffA);
;             PG8_WAIT_V(8); PG8_WAIT_L(0); PG8_BAR; PG8_MMA(1, 0, At, B0); PG8_MMA(1, 1, At, B1); PG8_BAR; PG8_SCHED;
.LBB0_215:
	ds_read_b128 v[130:133], v240
	ds_read_b128 v[146:149], v240 offset:1024
	ds_read_b128 v[150:153], v240 offset:2048
	ds_read_b128 v[154:157], v240 offset:3072
	ds_read_b128 v[162:165], v241
	ds_read_b128 v[166:169], v241 offset:1024
	ds_read_b128 v[170:173], v241 offset:2048
	ds_read_b128 v[174:177], v241 offset:3072
	s_add_i32 m0, s31, 0xc000
	ds_read_b128 v[182:185], v161
	ds_read_b128 v[186:189], v161 offset:1024
	ds_read_b128 v[190:193], v161 offset:2048
	ds_read_b128 v[216:219], v161 offset:3072
	ds_read_b128 v[220:223], v161 offset:4096
	ds_read_b128 v[224:227], v161 offset:5120
	ds_read_b128 v[228:231], v161 offset:6144
	ds_read_b128 v[236:239], v161 offset:7168
	global_load_lds_dwordx4 v142, s[8:9]
	s_add_i32 m0, s31, 0xe000
	s_nop 0
	global_load_lds_dwordx4 v144, s[8:9]
	s_add_i32 s92, s26, 2
	s_add_u32 s93, s8, 0x80
	s_addc_u32 s27, s9, 0
	s_add_i32 s22, 0, 0x10000
	s_cmp_eq_u32 s11, s26
	s_cselect_b32 s27, s1, s27
	s_cselect_b32 s26, s0, s93
	s_cselect_b32 vcc_hi, s17, s35
	s_cselect_b32 vcc_lo, s16, s34
	s_add_i32 s23, 0, 0x14000
	s_waitcnt vmcnt(8)
	s_waitcnt lgkmcnt(0)
	s_barrier
	v_mfma_f32_16x16x32_bf16 v[126:129], v[130:133], v[182:185], v[126:129]
	v_mfma_f32_16x16x32_bf16 v[122:125], v[150:153], v[182:185], v[122:125]
	v_mfma_f32_16x16x32_bf16 v[110:113], v[130:133], v[190:193], v[110:113]
	v_mfma_f32_16x16x32_bf16 v[106:109], v[150:153], v[190:193], v[106:109]
	v_mfma_f32_16x16x32_bf16 v[94:97], v[130:133], v[220:223], v[94:97]
	v_mfma_f32_16x16x32_bf16 v[90:93], v[150:153], v[220:223], v[90:93]
	v_mfma_f32_16x16x32_bf16 v[78:81], v[130:133], v[228:231], v[78:81]
	v_mfma_f32_16x16x32_bf16 v[74:77], v[150:153], v[228:231], v[74:77]
	v_mfma_f32_16x16x32_bf16 v[126:129], v[146:149], v[186:189], v[126:129]
	v_mfma_f32_16x16x32_bf16 v[122:125], v[154:157], v[186:189], v[122:125]
	v_mfma_f32_16x16x32_bf16 v[110:113], v[146:149], v[216:219], v[110:113]
	v_mfma_f32_16x16x32_bf16 v[106:109], v[154:157], v[216:219], v[106:109]
	v_mfma_f32_16x16x32_bf16 v[94:97], v[146:149], v[224:227], v[94:97]
	v_mfma_f32_16x16x32_bf16 v[90:93], v[154:157], v[224:227], v[90:93]
	v_mfma_f32_16x16x32_bf16 v[78:81], v[146:149], v[236:239], v[78:81]
	v_mfma_f32_16x16x32_bf16 v[74:77], v[154:157], v[236:239], v[74:77]
	v_mfma_f32_16x16x32_bf16 v[118:121], v[162:165], v[182:185], v[118:121]
	v_mfma_f32_16x16x32_bf16 v[114:117], v[170:173], v[182:185], v[114:117]
	v_mfma_f32_16x16x32_bf16 v[102:105], v[162:165], v[190:193], v[102:105]
	v_mfma_f32_16x16x32_bf16 v[98:101], v[170:173], v[190:193], v[98:101]
	v_mfma_f32_16x16x32_bf16 v[86:89], v[162:165], v[220:223], v[86:89]
	v_mfma_f32_16x16x32_bf16 v[82:85], v[170:173], v[220:223], v[82:85]
	v_mfma_f32_16x16x32_bf16 v[70:73], v[162:165], v[228:231], v[70:73]
	v_mfma_f32_16x16x32_bf16 v[66:69], v[170:173], v[228:231], v[66:69]
	v_mfma_f32_16x16x32_bf16 v[118:121], v[166:169], v[186:189], v[118:121]
	v_mfma_f32_16x16x32_bf16 v[114:117], v[174:177], v[186:189], v[114:117]
	v_mfma_f32_16x16x32_bf16 v[102:105], v[166:169], v[216:219], v[102:105]
	v_mfma_f32_16x16x32_bf16 v[98:101], v[174:177], v[216:219], v[98:101]
	v_mfma_f32_16x16x32_bf16 v[86:89], v[166:169], v[224:227], v[86:89]
	v_mfma_f32_16x16x32_bf16 v[82:85], v[174:177], v[224:227], v[82:85]
	v_mfma_f32_16x16x32_bf16 v[70:73], v[166:169], v[236:239], v[70:73]
	v_mfma_f32_16x16x32_bf16 v[66:69], v[174:177], v[236:239], v[66:69]
	s_barrier
	s_add_i32 s22, s22, s30
	s_mov_b32 m0, s22
	ds_read_b128 v[182:185], v161 offset:16384
	ds_read_b128 v[186:189], v161 offset:17408
	ds_read_b128 v[190:193], v161 offset:18432
	ds_read_b128 v[216:219], v161 offset:19456
	ds_read_b128 v[220:223], v161 offset:20480
	ds_read_b128 v[224:227], v161 offset:21504
	ds_read_b128 v[228:231], v161 offset:22528
	ds_read_b128 v[236:239], v161 offset:23552
	global_load_lds_dwordx4 v136, vcc
	s_add_i32 m0, s22, 0x2000
	s_add_i32 s22, s23, s30
	global_load_lds_dwordx4 v140, vcc
	s_mov_b32 m0, s22
	s_nop 0
	global_load_lds_dwordx4 v253, vcc
	s_add_i32 m0, s22, 0x2000
	s_nop 0
	global_load_lds_dwordx4 v254, vcc
	s_mov_b32 m0, s31
	s_nop 0
	global_load_lds_dwordx4 v134, s[26:27]
	s_mov_b32 m0, s14
	s_nop 0
	global_load_lds_dwordx4 v138, s[26:27]
	s_waitcnt vmcnt(8)
	s_waitcnt lgkmcnt(0)
	s_barrier
	v_mfma_f32_16x16x32_bf16 v[62:65], v[130:133], v[182:185], v[62:65]
	v_mfma_f32_16x16x32_bf16 v[58:61], v[150:153], v[182:185], v[58:61]
	v_mfma_f32_16x16x32_bf16 v[46:49], v[130:133], v[190:193], v[46:49]
	v_mfma_f32_16x16x32_bf16 v[42:45], v[150:153], v[190:193], v[42:45]
	v_mfma_f32_16x16x32_bf16 v[30:33], v[130:133], v[220:223], v[30:33]
	v_mfma_f32_16x16x32_bf16 v[26:29], v[150:153], v[220:223], v[26:29]
	v_mfma_f32_16x16x32_bf16 v[14:17], v[130:133], v[228:231], v[14:17]
	v_mfma_f32_16x16x32_bf16 v[10:13], v[150:153], v[228:231], v[10:13]
	v_mfma_f32_16x16x32_bf16 v[62:65], v[146:149], v[186:189], v[62:65]
	v_mfma_f32_16x16x32_bf16 v[58:61], v[154:157], v[186:189], v[58:61]
	v_mfma_f32_16x16x32_bf16 v[46:49], v[146:149], v[216:219], v[46:49]
	v_mfma_f32_16x16x32_bf16 v[42:45], v[154:157], v[216:219], v[42:45]
	v_mfma_f32_16x16x32_bf16 v[30:33], v[146:149], v[224:227], v[30:33]
	v_mfma_f32_16x16x32_bf16 v[26:29], v[154:157], v[224:227], v[26:29]
	v_mfma_f32_16x16x32_bf16 v[14:17], v[146:149], v[236:239], v[14:17]
	v_mfma_f32_16x16x32_bf16 v[10:13], v[154:157], v[236:239], v[10:13]
	v_mfma_f32_16x16x32_bf16 v[54:57], v[162:165], v[182:185], v[54:57]
	v_mfma_f32_16x16x32_bf16 v[50:53], v[170:173], v[182:185], v[50:53]
	v_mfma_f32_16x16x32_bf16 v[38:41], v[162:165], v[190:193], v[38:41]
	v_mfma_f32_16x16x32_bf16 v[34:37], v[170:173], v[190:193], v[34:37]
	v_mfma_f32_16x16x32_bf16 v[22:25], v[162:165], v[220:223], v[22:25]
	v_mfma_f32_16x16x32_bf16 v[18:21], v[170:173], v[220:223], v[18:21]
	v_mfma_f32_16x16x32_bf16 v[6:9], v[162:165], v[228:231], v[6:9]
	v_mfma_f32_16x16x32_bf16 v[2:5], v[170:173], v[228:231], v[2:5]
	v_mfma_f32_16x16x32_bf16 v[54:57], v[166:169], v[186:189], v[54:57]
	v_mfma_f32_16x16x32_bf16 v[50:53], v[174:177], v[186:189], v[50:53]
	v_mfma_f32_16x16x32_bf16 v[38:41], v[166:169], v[216:219], v[38:41]
	v_mfma_f32_16x16x32_bf16 v[34:37], v[174:177], v[216:219], v[34:37]
	v_mfma_f32_16x16x32_bf16 v[22:25], v[166:169], v[224:227], v[22:25]
	v_mfma_f32_16x16x32_bf16 v[18:21], v[174:177], v[224:227], v[18:21]
	v_mfma_f32_16x16x32_bf16 v[6:9], v[166:169], v[236:239], v[6:9]
	v_mfma_f32_16x16x32_bf16 v[2:5], v[174:177], v[236:239], v[2:5]
	s_barrier
; #define PG8_STAGE(bufoff, gbase, voff) do { _Pragma("unroll") for (int _i = 0; _i < 2; ++_i) \
;         __builtin_amdgcn_global_load_lds((const unsigned*)((const char*)(gbase) + (voff)[_i]), (LAS unsigned*)(lds + (bufoff) + ldsw + _i * 8192), 16, 0, 0); } while (0)
; #define PG8_LDA(dst, b, h) do { _Pragma("unroll") for (int m = 0; m < 4; ++m) _Pragma("unroll") for (int k = 0; k < 2; ++k) dst[m][k] = *(const LAS bf16x8*)(lds + PG8_SA(b, h) + aoff + m * 2048 + k * 1024); } while (0)
; #define PG8_LDB(dst, b, h) do { _Pragma("unroll") for (int n = 0; n < 2; ++n) _Pragma("unroll") for (int k = 0; k < 2; ++k) dst[n][k] = *(const LAS bf16x8*)(lds + PG8_SB(b, h) + boff + n * 2048 + k * 1024); } while (0)
; #define PG8_MMA(ai, bj, At, Bt) do { __builtin_amdgcn_s_setprio(1); _Pragma("unroll") for (int m = 0; m < 4; ++m) _Pragma("unroll") for (int n = 0; n < 2; ++n) _Pragma("unroll") for (int k = 0; k < 2; ++k) \
;         acc[ai][bj][m][n] = __builtin_amdgcn_mfma_f32_16x16x32_bf16(Bt[n][k], At[m][k], acc[ai][bj][m][n], 0, 0, 0); __builtin_amdgcn_s_setprio(0); } while (0)
; #define PG8_WAIT_V(n) asm volatile("s_waitcnt vmcnt(" #n ")" ::: "memory")
; #define PG8_WAIT_L(n) asm volatile("s_waitcnt lgkmcnt(" #n ")" ::: "memory")
; #define PG8_BAR __builtin_amdgcn_s_barrier()
; #define PG8_SCHED __builtin_amdgcn_sched_barrier(0)
; __device__ __forceinline__ void gemm_phase(LAS unsigned char* lds, const GemmD g, const Sched& S, const Epi& E) {
;     ...
;             PG8_LDB(B0, 1, 0); PG8_LDB(B1, 1, 1); PG8_SCHED; PG8_LDA(At, 1, 0); PG8_STAGE(PG8_SA(0, 1), a2 + hstepA, voffA);
;             PG8_WAIT_V(8); PG8_WAIT_L(0); PG8_BAR; PG8_MMA(0, 0, At, B0); PG8_MMA(0, 1, At, B1); PG8_BAR; PG8_SCHED;
;             PG8_LDA(At, 1, 1); PG8_STAGE(PG8_SB(1, 0), b3, voffB); PG8_STAGE(PG8_SB(1, 1), b3 + hstepB, voffB); PG8_STAGE(PG8_SA(1, 0), a3, voffA);
;             PG8_WAIT_V(8); PG8_WAIT_L(0); PG8_BAR; PG8_MMA(1, 0, At, B0); PG8_MMA(1, 1, At, B1); PG8_BAR; PG8_SCHED;
;         }
	s_add_i32 s22, 0, 0x18000
	s_add_i32 s23, 0, 0x1c000
	ds_read_b128 v[130:133], v242
	ds_read_b128 v[146:149], v242 offset:1024
	ds_read_b128 v[150:153], v242 offset:2048
	ds_read_b128 v[154:157], v242 offset:3072
	ds_read_b128 v[162:165], v243
	ds_read_b128 v[166:169], v243 offset:1024
	ds_read_b128 v[170:173], v243 offset:2048
	ds_read_b128 v[174:177], v243 offset:3072
	s_mov_b32 m0, s15
	ds_read_b128 v[182:185], v161 offset:32768
	ds_read_b128 v[186:189], v161 offset:33792
	ds_read_b128 v[190:193], v161 offset:34816
	ds_read_b128 v[216:219], v161 offset:35840
	ds_read_b128 v[220:223], v161 offset:36864
	ds_read_b128 v[224:227], v161 offset:37888
	ds_read_b128 v[228:231], v161 offset:38912
	ds_read_b128 v[236:239], v161 offset:39936
	global_load_lds_dwordx4 v142, s[26:27]
	s_mov_b32 m0, s10
	s_nop 0
	global_load_lds_dwordx4 v144, s[26:27]
	s_waitcnt vmcnt(8)
	s_waitcnt lgkmcnt(0)
	s_barrier
	v_mfma_f32_16x16x32_bf16 v[126:129], v[130:133], v[182:185], v[126:129]
	v_mfma_f32_16x16x32_bf16 v[122:125], v[150:153], v[182:185], v[122:125]
	v_mfma_f32_16x16x32_bf16 v[110:113], v[130:133], v[190:193], v[110:113]
	v_mfma_f32_16x16x32_bf16 v[106:109], v[150:153], v[190:193], v[106:109]
	v_mfma_f32_16x16x32_bf16 v[94:97], v[130:133], v[220:223], v[94:97]
	v_mfma_f32_16x16x32_bf16 v[90:93], v[150:153], v[220:223], v[90:93]
	v_mfma_f32_16x16x32_bf16 v[78:81], v[130:133], v[228:231], v[78:81]
	v_mfma_f32_16x16x32_bf16 v[74:77], v[150:153], v[228:231], v[74:77]
	v_mfma_f32_16x16x32_bf16 v[126:129], v[146:149], v[186:189], v[126:129]
	v_mfma_f32_16x16x32_bf16 v[122:125], v[154:157], v[186:189], v[122:125]
	v_mfma_f32_16x16x32_bf16 v[110:113], v[146:149], v[216:219], v[110:113]
	v_mfma_f32_16x16x32_bf16 v[106:109], v[154:157], v[216:219], v[106:109]
	v_mfma_f32_16x16x32_bf16 v[94:97], v[146:149], v[224:227], v[94:97]
	v_mfma_f32_16x16x32_bf16 v[90:93], v[154:157], v[224:227], v[90:93]
	v_mfma_f32_16x16x32_bf16 v[78:81], v[146:149], v[236:239], v[78:81]
	v_mfma_f32_16x16x32_bf16 v[74:77], v[154:157], v[236:239], v[74:77]
	v_mfma_f32_16x16x32_bf16 v[118:121], v[162:165], v[182:185], v[118:121]
	v_mfma_f32_16x16x32_bf16 v[114:117], v[170:173], v[182:185], v[114:117]
	v_mfma_f32_16x16x32_bf16 v[102:105], v[162:165], v[190:193], v[102:105]
	v_mfma_f32_16x16x32_bf16 v[98:101], v[170:173], v[190:193], v[98:101]
	v_mfma_f32_16x16x32_bf16 v[86:89], v[162:165], v[220:223], v[86:89]
	v_mfma_f32_16x16x32_bf16 v[82:85], v[170:173], v[220:223], v[82:85]
	v_mfma_f32_16x16x32_bf16 v[70:73], v[162:165], v[228:231], v[70:73]
	v_mfma_f32_16x16x32_bf16 v[66:69], v[170:173], v[228:231], v[66:69]
	v_mfma_f32_16x16x32_bf16 v[118:121], v[166:169], v[186:189], v[118:121]
	v_mfma_f32_16x16x32_bf16 v[114:117], v[174:177], v[186:189], v[114:117]
	v_mfma_f32_16x16x32_bf16 v[102:105], v[166:169], v[216:219], v[102:105]
	v_mfma_f32_16x16x32_bf16 v[98:101], v[174:177], v[216:219], v[98:101]
	v_mfma_f32_16x16x32_bf16 v[86:89], v[166:169], v[224:227], v[86:89]
	v_mfma_f32_16x16x32_bf16 v[82:85], v[174:177], v[224:227], v[82:85]
	v_mfma_f32_16x16x32_bf16 v[70:73], v[166:169], v[236:239], v[70:73]
	v_mfma_f32_16x16x32_bf16 v[66:69], v[174:177], v[236:239], v[66:69]
	s_barrier
	s_add_i32 s22, s22, s30
	s_add_u32 vcc_lo, vcc_lo, s84
	s_addc_u32 vcc_hi, vcc_hi, s85
	s_add_u32 s26, s26, s84
	s_addc_u32 s27, s27, s85
	s_mov_b32 m0, s22
	ds_read_b128 v[182:185], v161 offset:49152
	ds_read_b128 v[186:189], v161 offset:50176
	ds_read_b128 v[190:193], v161 offset:51200
	ds_read_b128 v[216:219], v161 offset:52224
	ds_read_b128 v[220:223], v161 offset:53248
	ds_read_b128 v[224:227], v161 offset:54272
	ds_read_b128 v[228:231], v161 offset:55296
	ds_read_b128 v[236:239], v161 offset:56320
	global_load_lds_dwordx4 v136, vcc
	s_add_i32 m0, s22, 0x2000
	s_add_i32 s22, s23, s30
	global_load_lds_dwordx4 v140, vcc
	s_mov_b32 m0, s22
	s_nop 0
	global_load_lds_dwordx4 v253, vcc
	s_add_i32 m0, s22, 0x2000
	s_nop 0
	global_load_lds_dwordx4 v254, vcc
	s_mov_b32 m0, s18
	s_nop 0
	global_load_lds_dwordx4 v134, s[26:27]
	s_mov_b32 m0, s19
	s_nop 0
	global_load_lds_dwordx4 v138, s[26:27]
	s_waitcnt vmcnt(8)
	s_waitcnt lgkmcnt(0)
	s_barrier
	v_mfma_f32_16x16x32_bf16 v[62:65], v[130:133], v[182:185], v[62:65]
	v_mfma_f32_16x16x32_bf16 v[58:61], v[150:153], v[182:185], v[58:61]
	v_mfma_f32_16x16x32_bf16 v[46:49], v[130:133], v[190:193], v[46:49]
	v_mfma_f32_16x16x32_bf16 v[42:45], v[150:153], v[190:193], v[42:45]
	v_mfma_f32_16x16x32_bf16 v[30:33], v[130:133], v[220:223], v[30:33]
	v_mfma_f32_16x16x32_bf16 v[26:29], v[150:153], v[220:223], v[26:29]
	v_mfma_f32_16x16x32_bf16 v[14:17], v[130:133], v[228:231], v[14:17]
	v_mfma_f32_16x16x32_bf16 v[10:13], v[150:153], v[228:231], v[10:13]
	v_mfma_f32_16x16x32_bf16 v[62:65], v[146:149], v[186:189], v[62:65]
	v_mfma_f32_16x16x32_bf16 v[58:61], v[154:157], v[186:189], v[58:61]
	v_mfma_f32_16x16x32_bf16 v[46:49], v[146:149], v[216:219], v[46:49]
	v_mfma_f32_16x16x32_bf16 v[42:45], v[154:157], v[216:219], v[42:45]
	v_mfma_f32_16x16x32_bf16 v[30:33], v[146:149], v[224:227], v[30:33]
	v_mfma_f32_16x16x32_bf16 v[26:29], v[154:157], v[224:227], v[26:29]
	v_mfma_f32_16x16x32_bf16 v[14:17], v[146:149], v[236:239], v[14:17]
	v_mfma_f32_16x16x32_bf16 v[10:13], v[154:157], v[236:239], v[10:13]
	v_mfma_f32_16x16x32_bf16 v[54:57], v[162:165], v[182:185], v[54:57]
	v_mfma_f32_16x16x32_bf16 v[50:53], v[170:173], v[182:185], v[50:53]
	v_mfma_f32_16x16x32_bf16 v[38:41], v[162:165], v[190:193], v[38:41]
	v_mfma_f32_16x16x32_bf16 v[34:37], v[170:173], v[190:193], v[34:37]
	v_mfma_f32_16x16x32_bf16 v[22:25], v[162:165], v[220:223], v[22:25]
	v_mfma_f32_16x16x32_bf16 v[18:21], v[170:173], v[220:223], v[18:21]
	v_mfma_f32_16x16x32_bf16 v[6:9], v[162:165], v[228:231], v[6:9]
	v_mfma_f32_16x16x32_bf16 v[2:5], v[170:173], v[228:231], v[2:5]
	v_mfma_f32_16x16x32_bf16 v[54:57], v[166:169], v[186:189], v[54:57]
	v_mfma_f32_16x16x32_bf16 v[50:53], v[174:177], v[186:189], v[50:53]
	v_mfma_f32_16x16x32_bf16 v[38:41], v[166:169], v[216:219], v[38:41]
	v_mfma_f32_16x16x32_bf16 v[34:37], v[174:177], v[216:219], v[34:37]
	v_mfma_f32_16x16x32_bf16 v[22:25], v[166:169], v[224:227], v[22:25]
	v_mfma_f32_16x16x32_bf16 v[18:21], v[174:177], v[224:227], v[18:21]
	v_mfma_f32_16x16x32_bf16 v[6:9], v[166:169], v[236:239], v[6:9]
	v_mfma_f32_16x16x32_bf16 v[2:5], v[174:177], v[236:239], v[2:5]
	s_barrier
	s_add_u32 s8, s8, 0x100
	s_addc_u32 s9, s9, 0
	s_add_u32 s34, s34, 0x100
	s_addc_u32 s35, s35, 0
	s_cmp_ge_u32 s92, s12
	s_mov_b32 s26, s92
	s_cbranch_scc0 .LBB0_215
